# SB phase: waves delayed by (7-w) sleeps so a workgroup's 8 query blocks hit the same K/V tiles together; F r-table: 8 loads in one batch
# speedup vs baseline: 1.0084x; 1.0084x over previous
.LBB0_237:
	s_or_b64 exec, exec, s[0:1]
	v_readlane_b32 s0, v254, 62
	s_cmp_eq_u32 s0, 0
	s_cselect_b64 s[24:25], -1, 0
	s_andn2_b64 vcc, exec, s[68:69]
	s_mov_b64 s[0:1], -1
	s_waitcnt lgkmcnt(0)
	s_barrier
	s_cbranch_vccnz .LBB0_240
	v_readfirstlane_b32 s100, v208
	s_lshr_b32 s100, s100, 6
	s_sub_u32 s100, 7, s100
	s_cmp_eq_u32 s100, 0
	s_cbranch_scc1 .Lsb_nodelay
.Lsb_delay:
	s_sleep 64
	s_sub_u32 s100, s100, 1
	s_cmp_lg_u32 s100, 0
	s_cbranch_scc1 .Lsb_delay
.Lsb_nodelay:
	v_readlane_b32 s0, v254, 8
	v_readlane_b32 s1, v254, 9
	s_andn2_b64 vcc, exec, s[0:1]
	v_readlane_b32 s0, v254, 6
	s_mov_b64 s[12:13], s[68:69]
	s_mov_b32 s14, s0
	s_mov_b32 s15, s0
	v_readlane_b32 s1, v254, 7
	s_cbranch_vccz .LBB0_247

.LBB0_498:
	v_cmp_gt_i64_e32 vcc, s[44:45], v[198:199]
	s_mov_b64 s[46:47], -1
	s_cbranch_vccnz .LBB0_497
	s_and_saveexec_b64 s[46:47], s[40:41]
	s_cbranch_execz .LBB0_496
	s_ashr_i32 s6, s44, 31
	s_lshr_b32 s6, s6, 29
	s_add_i32 s6, s44, s6
	s_ashr_i32 s7, s6, 3
	s_and_b32 s6, s6, -8
	s_sub_i32 s6, s44, s6
	s_cmp_lt_i32 s6, 0
	s_movk_i32 s9, 0x161
	s_cselect_b32 s9, s9, 0x160
	s_mul_i32 s6, s6, s9
	s_add_i32 s6, s6, s7
	s_mul_hi_i32 s7, s6, 0x2e8ba2e9
	s_lshr_b32 s9, s7, 31
	s_ashr_i32 s7, s7, 6
	s_add_i32 s7, s7, s9
	s_mul_i32 s9, s7, 0x160
	s_lshl_b32 s7, s7, 3
	s_sub_i32 s6, s6, s9
	s_sub_i32 s9, 64, s7
	s_min_i32 s9, s9, 8
	s_abs_i32 s9, s9
	v_cvt_f32_u32_e32 v3, s9
	s_sub_i32 s11, 0, s9
	s_ashr_i32 s10, s6, 31
	s_abs_i32 s6, s6
	v_rcp_iflag_f32_e32 v3, v3
	s_nop 0
	v_mul_f32_e32 v3, 0x4f7ffffe, v3
	v_cvt_u32_f32_e32 v3, v3
	s_nop 0
	v_readfirstlane_b32 s12, v3
	s_mul_i32 s11, s11, s12
	s_mul_hi_u32 s11, s12, s11
	s_add_i32 s12, s12, s11
	s_mul_hi_u32 s11, s6, s12
	s_mul_i32 s11, s11, s9
	s_sub_i32 s6, s6, s11
	s_sub_i32 s11, s6, s9
	s_cmp_ge_u32 s6, s9
	s_cselect_b32 s6, s11, s6
	s_sub_i32 s11, s6, s9
	s_cmp_ge_u32 s6, s9
	s_cselect_b32 s6, s11, s6
	s_xor_b32 s6, s6, s10
	s_sub_i32 s6, s6, s10
	s_add_i32 s6, s6, s7
	v_lshl_add_u32 v4, s6, 8, v0
	v_ashrrev_i32_e32 v5, 31, v4
	v_lshlrev_b64 v[4:5], 7, v[4:5]
	v_lshl_add_u64 v[20:21], s[0:1], 0, v[4:5]
	global_load_dwordx4 v[4:7], v[20:21], off offset:48
	global_load_dwordx4 v[8:11], v[20:21], off offset:32
	global_load_dwordx4 v[12:15], v[20:21], off
	global_load_dwordx4 v[16:19], v[20:21], off offset:16
	global_load_dwordx4 v[26:29], v[20:21], off offset:112
	global_load_dwordx4 v[30:33], v[20:21], off offset:96
	global_load_dwordx4 v[34:37], v[20:21], off offset:80
	global_load_dwordx4 v[38:41], v[20:21], off offset:64
	s_waitcnt vmcnt(0)
	v_pk_add_f32 v[14:15], v[14:15], v[18:19]
	v_pk_add_f32 v[12:13], v[12:13], v[16:17]
	v_pk_add_f32 v[10:11], v[14:15], v[10:11]
	v_pk_add_f32 v[8:9], v[12:13], v[8:9]
	v_pk_add_f32 v[22:23], v[10:11], v[6:7]
	v_pk_add_f32 v[24:25], v[8:9], v[4:5]
	v_pk_add_f32 v[18:19], v[22:23], v[40:41]
	v_pk_add_f32 v[16:17], v[24:25], v[38:39]
	v_pk_add_f32 v[14:15], v[18:19], v[36:37]
	v_pk_add_f32 v[12:13], v[16:17], v[34:35]
	v_pk_add_f32 v[10:11], v[14:15], v[32:33]
	v_pk_add_f32 v[8:9], v[12:13], v[30:31]
	v_pk_add_f32 v[6:7], v[10:11], v[28:29]
	v_pk_add_f32 v[4:5], v[8:9], v[26:27]
	s_nop 0
	v_pk_mov_b32 v[8:9], v[4:5], v[6:7] op_sel:[1,0]
	v_mov_b32_e32 v5, v7
	v_pk_add_f32 v[4:5], v[8:9], v[4:5]
	s_nop 0
	v_add_f32_e32 v3, v4, v5
	v_mov_b32_e32 v4, 0x3727c5ac
	v_fmamk_f32 v3, v3, 0x3a000000, v4
	v_rsq_f32_e32 v3, v3
	v_add_u32_e32 v4, s8, v2
	ds_write_b32 v4, v3 offset:14336
	s_branch .LBB0_496

	.amdhsa_kernel _Z8yoco_fwd4Args
		.amdhsa_group_segment_fixed_size 0
		.amdhsa_private_segment_fixed_size 0
		.amdhsa_kernarg_size 424
		.amdhsa_user_sgpr_count 2
		.amdhsa_user_sgpr_dispatch_ptr 0
		.amdhsa_user_sgpr_queue_ptr 0
		.amdhsa_user_sgpr_kernarg_segment_ptr 1
		.amdhsa_user_sgpr_dispatch_id 0
		.amdhsa_user_sgpr_kernarg_preload_length 0
		.amdhsa_user_sgpr_kernarg_preload_offset 0
		.amdhsa_user_sgpr_private_segment_size 0
		.amdhsa_uses_dynamic_stack 0
		.amdhsa_enable_private_segment 0
		.amdhsa_system_sgpr_workgroup_id_x 1
		.amdhsa_system_sgpr_workgroup_id_y 0
		.amdhsa_system_sgpr_workgroup_id_z 0
		.amdhsa_system_sgpr_workgroup_info 0
		.amdhsa_system_vgpr_workitem_id 2
		.amdhsa_next_free_vgpr 256
		.amdhsa_next_free_sgpr 102
		.amdhsa_accum_offset 256
		.amdhsa_reserve_vcc 1
		.amdhsa_float_round_mode_32 0
		.amdhsa_float_round_mode_16_64 0
		.amdhsa_float_denorm_mode_32 3
		.amdhsa_float_denorm_mode_16_64 3
		.amdhsa_dx10_clamp 1
		.amdhsa_ieee_mode 1
		.amdhsa_fp16_overflow 0
		.amdhsa_tg_split 0
		.amdhsa_exception_fp_ieee_invalid_op 0
		.amdhsa_exception_fp_denorm_src 0
		.amdhsa_exception_fp_ieee_div_zero 0
		.amdhsa_exception_fp_ieee_overflow 0
		.amdhsa_exception_fp_ieee_underflow 0
		.amdhsa_exception_fp_ieee_inexact 0
		.amdhsa_exception_int_div_zero 0
	.end_amdhsa_kernel

amdhsa.kernels:
  - .agpr_count:     0
    .args:
      - .offset:         0
        .size:           168
        .value_kind:     by_value
      - .offset:         168
        .size:           4
        .value_kind:     hidden_block_count_x
      - .offset:         172
        .size:           4
        .value_kind:     hidden_block_count_y
      - .offset:         176
        .size:           4
        .value_kind:     hidden_block_count_z
      - .offset:         180
        .size:           2
        .value_kind:     hidden_group_size_x
      - .offset:         182
        .size:           2
        .value_kind:     hidden_group_size_y
      - .offset:         184
        .size:           2
        .value_kind:     hidden_group_size_z
      - .offset:         186
        .size:           2
        .value_kind:     hidden_remainder_x
      - .offset:         188
        .size:           2
        .value_kind:     hidden_remainder_y
      - .offset:         190
        .size:           2
        .value_kind:     hidden_remainder_z
      - .offset:         208
        .size:           8
        .value_kind:     hidden_global_offset_x
      - .offset:         216
        .size:           8
        .value_kind:     hidden_global_offset_y
      - .offset:         224
        .size:           8
        .value_kind:     hidden_global_offset_z
      - .offset:         232
        .size:           2
        .value_kind:     hidden_grid_dims
      - .offset:         256
        .size:           8
        .value_kind:     hidden_multigrid_sync_arg
      - .offset:         288
        .size:           4
        .value_kind:     hidden_dynamic_lds_size
    .group_segment_fixed_size: 0
    .kernarg_segment_align: 8
    .kernarg_segment_size: 424
    .language:       OpenCL C
    .language_version:
      - 2
      - 0
    .max_flat_workgroup_size: 512
    .name:           _Z8yoco_fwd4Args
    .private_segment_fixed_size: 0
    .sgpr_count:     108
    .sgpr_spill_count: 197
    .symbol:         _Z8yoco_fwd4Args.kd
    .uniform_work_group_size: 1
    .uses_dynamic_stack: false
    .vgpr_count:     256
    .vgpr_spill_count: 0
    .wavefront_size: 64
